# producer ds_write_b128 spaced apart with 5x s_nop 7
# baseline (speedup 1.0000x reference)
; #define LAS __attribute__((address_space(3)))
; __device__ __forceinline__ float f16_to_f(unsigned short h) { return (float)__builtin_bit_cast(_Float16, h); }
; __device__ __forceinline__ float scan_prepare(const ScanRegs& R, const u32x2 qr_, const u32x2 qk_, const u32x2 qv_, LAS float* slot, int cq, const f32x4 mur, const f32x4 muk, const f32x4 muv, const f32x4 kkc, const f32x4 kac, const f32x4 rkc) {
;     float pr[4], pk[4], pv[4], qr[4], qk[4], qv[4], av[4], om[4];
;     unpack4(R.pr, pr); unpack4(R.pk, pk); unpack4(R.pv, pv); unpack4(qr_, qr); unpack4(qk_, qk); unpack4(qv_, qv); unpack4(R.as, av);
;     om[0] = f16_to_f((unsigned short)(R.wl.x & 0xffffu)); om[1] = f16_to_f((unsigned short)(R.wl.x >> 16)); om[2] = f16_to_f((unsigned short)(R.wl.y & 0xffffu)); om[3] = f16_to_f((unsigned short)(R.wl.y >> 16));
;     float rr[4], vv[4], kn[4], k2[4], dec[4], bu[4];
;     float ssq = 0.f, bon = 0.f, c1 = 0.f, c2 = 0.f;
; #pragma unroll
;     for (int j = 0; j < 4; ++j) {
;         rr[j] = pr[j] + (qr[j] - pr[j]) * mur[j]; const float kk0 = pk[j] + (qk[j] - pk[j]) * muk[j]; vv[j] = pv[j] + (qv[j] - pv[j]) * muv[j];
;         dec[j] = 1.0f - om[j];
;         kn[j] = kk0 * kkc[j]; ssq += kn[j] * kn[j];
;         k2[j] = kk0 * (1.0f + (av[j] - 1.0f) * kac[j]);
;         const float t = rr[j] * k2[j]; bon += t * rkc[j]; c2 += t;
;         bu[j] = kn[j] * av[j]; c1 += bu[j] * rr[j];
;     }
;     ssq += dpp_f<0x121>(ssq); bon += dpp_f<0x121>(bon); c1 += dpp_f<0x121>(c1); c2 += dpp_f<0x121>(c2);
;     ssq += dpp_f<0x122>(ssq); bon += dpp_f<0x122>(bon); c1 += dpp_f<0x122>(c1); c2 += dpp_f<0x122>(c2);
;     ssq += dpp_f<0x124>(ssq); bon += dpp_f<0x124>(bon); c1 += dpp_f<0x124>(c1); c2 += dpp_f<0x124>(c2);
;     ssq += dpp_f<0x128>(ssq); bon += dpp_f<0x128>(bon); c1 += dpp_f<0x128>(c1); c2 += dpp_f<0x128>(c2);
;     const float inv = __builtin_amdgcn_rsqf(fmaxf(ssq, 1e-24f));
;     f32x4 o_al, o_be, o_wr;
; #pragma unroll
;     for (int j = 0; j < 4; ++j) { o_al[j] = -(kn[j] * inv); o_be[j] = bu[j] * inv; o_wr[j] = dec[j] * rr[j]; }
;     LAS f32x4* s4 = (LAS f32x4*)slot;
;     s4[cq] = (f32x4){dec[0], dec[1], dec[2], dec[3]}; s4[16 + cq] = (f32x4){k2[0], k2[1], k2[2], k2[3]}; s4[32 + cq] = o_al; s4[48 + cq] = o_be; s4[64 + cq] = o_wr;
;     s4[80 + cq] = (f32x4){vv[0], vv[1], vv[2], vv[3]};
;     if (cq == 0) *(LAS f32x2*)(slot + 384) = (f32x2){c1 * inv, c2};
.LBB0_1109:
	s_waitcnt vmcnt(8)
	v_lshlrev_b32_e32 v108, 16, v46
	v_and_b32_e32 v109, 0xffff0000, v46
	v_lshlrev_b32_e32 v110, 16, v38
	v_and_b32_e32 v111, 0xffff0000, v38
	v_pk_add_f32 v[110:111], v[110:111], v[108:109] neg_lo:[0,1] neg_hi:[0,1]
	v_lshlrev_b32_e32 v140, 16, v39
	v_pk_fma_f32 v[144:145], v[6:7], v[110:111], v[108:109]
	v_lshlrev_b32_e32 v110, 16, v47
	v_and_b32_e32 v111, 0xffff0000, v47
	v_and_b32_e32 v141, 0xffff0000, v39
	v_pk_add_f32 v[140:141], v[140:141], v[110:111] neg_lo:[0,1] neg_hi:[0,1]
	v_lshlrev_b32_e32 v118, 16, v40
	v_and_b32_e32 v119, 0xffff0000, v40
	v_pk_fma_f32 v[146:147], v[8:9], v[140:141], v[110:111]
	v_lshlrev_b32_e32 v140, 16, v34
	v_and_b32_e32 v141, 0xffff0000, v34
	s_waitcnt vmcnt(3)
	v_lshlrev_b32_e32 v142, 16, v48
	v_and_b32_e32 v143, 0xffff0000, v48
	v_pk_add_f32 v[140:141], v[140:141], v[118:119] neg_lo:[0,1] neg_hi:[0,1]
	v_pk_add_f32 v[148:149], v[142:143], -1.0 op_sel_hi:[1,0]
	v_pk_fma_f32 v[140:141], v[2:3], v[140:141], v[118:119]
	v_pk_fma_f32 v[148:149], v[18:19], v[148:149], 1.0 op_sel_hi:[1,1,0]
	v_pk_mul_f32 v[154:155], v[14:15], v[140:141]
	v_pk_mul_f32 v[148:149], v[148:149], v[140:141]
	v_cvt_f32_f16_sdwa v141, v44 dst_sel:DWORD dst_unused:UNUSED_PAD src0_sel:WORD_1
	v_cvt_f32_f16_e32 v140, v44
	v_lshlrev_b32_e32 v114, 16, v36
	v_and_b32_e32 v115, 0xffff0000, v36
	v_lshlrev_b32_e32 v156, 16, v42
	v_and_b32_e32 v157, 0xffff0000, v42
	v_pk_add_f32 v[152:153], v[140:141], 1.0 op_sel_hi:[1,0] neg_lo:[1,0] neg_hi:[1,0]
	v_pk_add_f32 v[140:141], v[156:157], v[114:115] neg_lo:[0,1] neg_hi:[0,1]
	v_lshlrev_b32_e32 v116, 16, v41
	v_pk_fma_f32 v[164:165], v[10:11], v[140:141], v[114:115]
	v_and_b32_e32 v117, 0xffff0000, v41
	v_pk_mul_f32 v[140:141], v[164:165], v[148:149]
	v_pk_mul_f32 v[150:151], v[154:155], v[154:155]
	v_fma_f32 v33, v22, v140, 0
	v_add_f32_e32 v28, 0, v140
	v_fmac_f32_e32 v33, v23, v141
	v_add_f32_e32 v168, v141, v28
	v_lshlrev_b32_e32 v140, 16, v35
	v_and_b32_e32 v141, 0xffff0000, v35
	v_pk_add_f32 v[140:141], v[140:141], v[116:117] neg_lo:[0,1] neg_hi:[0,1]
	v_add_f32_e32 v28, v150, v151
	v_pk_fma_f32 v[140:141], v[4:5], v[140:141], v[116:117]
	v_pk_mul_f32 v[142:143], v[154:155], v[142:143]
	v_pk_mul_f32 v[158:159], v[16:17], v[140:141]
	v_pk_mul_f32 v[156:157], v[164:165], v[142:143]
	v_pk_mul_f32 v[160:161], v[158:159], v[158:159]
	v_add_f32_e32 v81, 0, v156
	v_add_f32_e32 v28, v160, v28
	v_add_f32_e32 v28, v161, v28
	v_add_f32_e32 v81, v157, v81
	v_lshlrev_b32_e32 v156, 16, v49
	v_add_f32_dpp v28, v28, v28 row_ror:1 row_mask:0xf bank_mask:0xf bound_ctrl:1
	v_and_b32_e32 v157, 0xffff0000, v49
	v_lshlrev_b32_e32 v112, 16, v37
	v_add_f32_dpp v28, v28, v28 row_ror:2 row_mask:0xf bank_mask:0xf bound_ctrl:1
	v_and_b32_e32 v113, 0xffff0000, v37
	v_pk_add_f32 v[162:163], v[156:157], -1.0 op_sel_hi:[1,0]
	v_add_f32_dpp v28, v28, v28 row_ror:4 row_mask:0xf bank_mask:0xf bound_ctrl:1
	v_pk_fma_f32 v[150:151], v[20:21], v[162:163], 1.0 op_sel_hi:[1,1,0]
	v_pk_mul_f32 v[164:165], v[164:165], 1.0 op_sel_hi:[1,0]
	v_add_f32_dpp v28, v28, v28 row_ror:8 row_mask:0xf bank_mask:0xf bound_ctrl:1
	v_max_f32_e32 v28, 0x179abe15, v28
	v_rsq_f32_e32 v28, v28
	v_pk_mul_f32 v[150:151], v[150:151], v[140:141]
	v_pk_mul_f32 v[140:141], v[158:159], v[156:157]
	v_pk_mul_f32 v[160:161], v[142:143], v[28:29] op_sel_hi:[1,0]
	v_lshlrev_b32_e32 v142, 16, v43
	v_and_b32_e32 v143, 0xffff0000, v43
	v_pk_add_f32 v[142:143], v[142:143], v[112:113] neg_lo:[0,1] neg_hi:[0,1]
	v_pk_mul_f32 v[162:163], v[140:141], v[28:29] op_sel_hi:[1,0]
	v_pk_fma_f32 v[166:167], v[12:13], v[142:143], v[112:113]
	v_pk_mul_f32 v[156:157], v[154:155], v[28:29] op_sel_hi:[1,0] neg_lo:[0,1] neg_hi:[0,1]
	v_pk_mul_f32 v[142:143], v[166:167], v[150:151]
	v_pk_mul_f32 v[140:141], v[166:167], v[140:141]
	v_fmac_f32_e32 v33, v24, v142
	v_add_f32_e32 v142, v142, v168
	v_add_f32_e32 v81, v140, v81
	v_cvt_f32_f16_sdwa v155, v45 dst_sel:DWORD dst_unused:UNUSED_PAD src0_sel:WORD_1
	v_cvt_f32_f16_e32 v154, v45
	v_fmac_f32_e32 v33, v25, v143
	v_add_f32_e32 v140, v143, v142
	v_add_f32_e32 v81, v141, v81
	v_add_f32_dpp v33, v33, v33 row_ror:1 row_mask:0xf bank_mask:0xf bound_ctrl:1
	v_add_f32_dpp v140, v140, v140 row_ror:1 row_mask:0xf bank_mask:0xf bound_ctrl:1
	v_add_f32_dpp v81, v81, v81 row_ror:1 row_mask:0xf bank_mask:0xf bound_ctrl:1
	v_add_f32_dpp v33, v33, v33 row_ror:2 row_mask:0xf bank_mask:0xf bound_ctrl:1
	v_add_f32_dpp v140, v140, v140 row_ror:2 row_mask:0xf bank_mask:0xf bound_ctrl:1
	v_add_f32_dpp v81, v81, v81 row_ror:2 row_mask:0xf bank_mask:0xf bound_ctrl:1
	v_add_f32_dpp v33, v33, v33 row_ror:4 row_mask:0xf bank_mask:0xf bound_ctrl:1
	v_add_f32_dpp v140, v140, v140 row_ror:4 row_mask:0xf bank_mask:0xf bound_ctrl:1
	v_add_f32_dpp v141, v81, v81 row_ror:4 row_mask:0xf bank_mask:0xf bound_ctrl:1
	v_mov_b32_e32 v142, 0
	v_mov_b32_e32 v143, 0
	v_mov_b32_e32 v81, 0
	v_pk_add_f32 v[154:155], v[154:155], 1.0 op_sel_hi:[1,0] neg_lo:[1,0] neg_hi:[1,0]
	v_mov_b32_dpp v142, v141 row_ror:8 row_mask:0xf bank_mask:0xf
	v_mov_b32_dpp v143, v140 row_ror:8 row_mask:0xf bank_mask:0xf
	v_mov_b32_dpp v81, v33 row_ror:8 row_mask:0xf bank_mask:0xf
	v_pk_mul_f32 v[158:159], v[158:159], v[28:29] op_sel_hi:[1,0] neg_lo:[0,1] neg_hi:[0,1]
	v_pk_mul_f32 v[166:167], v[166:167], 1.0 op_sel_hi:[1,0]
	ds_write_b128 v127, v[152:155] offset:50176
	s_nop 7
	s_nop 7
	s_nop 7
	s_nop 7
	s_nop 7
	ds_write_b128 v127, v[148:151] offset:50432
	s_nop 7
	s_nop 7
	s_nop 7
	s_nop 7
	s_nop 7
	ds_write_b128 v127, v[156:159] offset:50688
	s_nop 7
	s_nop 7
	s_nop 7
	s_nop 7
	s_nop 7
	ds_write_b128 v127, v[160:163] offset:50944
	s_nop 7
	s_nop 7
	s_nop 7
	s_nop 7
	s_nop 7
	ds_write_b128 v127, v[164:167] offset:51200
	s_nop 7
	s_nop 7
	s_nop 7
	s_nop 7
	s_nop 7
	ds_write_b128 v127, v[144:147] offset:51456
	s_nop 7
	s_nop 7
	s_nop 7
	s_nop 7
	s_nop 7
	s_and_saveexec_b64 s[52:53], s[4:5]
	v_add_f32_e32 v141, v141, v142
	v_mul_f32_e32 v142, v141, v28
	v_add_f32_e32 v143, v140, v143
	ds_write_b64 v126, v[142:143] offset:51712
	s_or_b64 exec, exec, s[52:53]
	s_waitcnt vmcnt(17)
; #define LAS __attribute__((address_space(3)))
; __device__ __forceinline__ float scan_prepare(const ScanRegs& R, const u32x2 qr_, const u32x2 qk_, const u32x2 qv_, LAS float* slot, int cq, const f32x4 mur, const f32x4 muk, const f32x4 muv, const f32x4 kkc, const f32x4 kac, const f32x4 rkc) {
;     float pr[4], pk[4], pv[4], qr[4], qk[4], qv[4], av[4], om[4];
;     unpack4(R.pr, pr); unpack4(R.pk, pk); unpack4(R.pv, pv); unpack4(qr_, qr); unpack4(qk_, qk); unpack4(qv_, qv); unpack4(R.as, av);
;     om[0] = f16_to_f((unsigned short)(R.wl.x & 0xffffu)); om[1] = f16_to_f((unsigned short)(R.wl.x >> 16)); om[2] = f16_to_f((unsigned short)(R.wl.y & 0xffffu)); om[3] = f16_to_f((unsigned short)(R.wl.y >> 16));
;     float rr[4], vv[4], kn[4], k2[4], dec[4], bu[4];
;     float ssq = 0.f, bon = 0.f, c1 = 0.f, c2 = 0.f;
; #pragma unroll
;     for (int j = 0; j < 4; ++j) {
;         rr[j] = pr[j] + (qr[j] - pr[j]) * mur[j]; const float kk0 = pk[j] + (qk[j] - pk[j]) * muk[j]; vv[j] = pv[j] + (qv[j] - pv[j]) * muv[j];
;         dec[j] = 1.0f - om[j];
;         kn[j] = kk0 * kkc[j]; ssq += kn[j] * kn[j];
;         k2[j] = kk0 * (1.0f + (av[j] - 1.0f) * kac[j]);
;         const float t = rr[j] * k2[j]; bon += t * rkc[j]; c2 += t;
;         bu[j] = kn[j] * av[j]; c1 += bu[j] * rr[j];
;     }
;     ssq += dpp_f<0x121>(ssq); bon += dpp_f<0x121>(bon); c1 += dpp_f<0x121>(c1); c2 += dpp_f<0x121>(c2);
;     ssq += dpp_f<0x122>(ssq); bon += dpp_f<0x122>(bon); c1 += dpp_f<0x122>(c1); c2 += dpp_f<0x122>(c2);
;     ssq += dpp_f<0x124>(ssq); bon += dpp_f<0x124>(bon); c1 += dpp_f<0x124>(c1); c2 += dpp_f<0x124>(c2);
;     ssq += dpp_f<0x128>(ssq); bon += dpp_f<0x128>(bon); c1 += dpp_f<0x128>(c1); c2 += dpp_f<0x128>(c2);
;     const float inv = __builtin_amdgcn_rsqf(fmaxf(ssq, 1e-24f));
;     f32x4 o_al, o_be, o_wr;
; #pragma unroll
;     for (int j = 0; j < 4; ++j) { o_al[j] = -(kn[j] * inv); o_be[j] = bu[j] * inv; o_wr[j] = dec[j] * rr[j]; }
;     LAS f32x4* s4 = (LAS f32x4*)slot;
;     s4[cq] = (f32x4){dec[0], dec[1], dec[2], dec[3]}; s4[16 + cq] = (f32x4){k2[0], k2[1], k2[2], k2[3]}; s4[32 + cq] = o_al; s4[48 + cq] = o_be; s4[64 + cq] = o_wr;
;     s4[80 + cq] = (f32x4){vv[0], vv[1], vv[2], vv[3]};
;     if (cq == 0) *(LAS f32x2*)(slot + 384) = (f32x2){c1 * inv, c2};
;     return bon;
; }
	v_lshlrev_b32_e32 v140, 16, v50
	v_and_b32_e32 v141, 0xffff0000, v50
	s_waitcnt vmcnt(2)
	v_lshlrev_b32_e32 v142, 16, v58
	v_and_b32_e32 v143, 0xffff0000, v58
	v_pk_add_f32 v[118:119], v[118:119], v[140:141] neg_lo:[0,1] neg_hi:[0,1]
	v_lshlrev_b32_e32 v150, 16, v59
	v_pk_fma_f32 v[118:119], v[2:3], v[118:119], v[140:141]
	v_pk_add_f32 v[140:141], v[142:143], -1.0 op_sel_hi:[1,0]
	v_pk_mul_f32 v[146:147], v[14:15], v[118:119]
	v_pk_fma_f32 v[140:141], v[18:19], v[140:141], 1.0 op_sel_hi:[1,1,0]
	v_pk_mul_f32 v[152:153], v[146:147], v[142:143]
	v_pk_mul_f32 v[140:141], v[140:141], v[118:119]
	v_cvt_f32_f16_sdwa v119, v52 dst_sel:DWORD dst_unused:UNUSED_PAD src0_sel:WORD_1
	v_cvt_f32_f16_e32 v118, v52
	s_waitcnt vmcnt(6)
	v_lshlrev_b32_e32 v142, 16, v82
	v_and_b32_e32 v143, 0xffff0000, v82
	v_pk_add_f32 v[114:115], v[114:115], v[142:143] neg_lo:[0,1] neg_hi:[0,1]
	v_pk_add_f32 v[144:145], v[118:119], 1.0 op_sel_hi:[1,0] neg_lo:[1,0] neg_hi:[1,0]
	v_pk_fma_f32 v[118:119], v[10:11], v[114:115], v[142:143]
	v_pk_mul_f32 v[148:149], v[146:147], v[146:147]
	v_pk_mul_f32 v[114:115], v[118:119], v[140:141]
	v_pk_mul_f32 v[142:143], v[118:119], v[152:153]
	v_fma_f32 v156, v22, v114, 0
	v_add_f32_e32 v28, 0, v114
	v_add_f32_e32 v114, 0, v142
	v_fmac_f32_e32 v156, v23, v115
	v_add_f32_e32 v157, v115, v28
	v_add_f32_e32 v164, v143, v114
	v_lshlrev_b32_e32 v114, 16, v51
	v_and_b32_e32 v115, 0xffff0000, v51
	v_pk_add_f32 v[116:117], v[116:117], v[114:115] neg_lo:[0,1] neg_hi:[0,1]
	v_add_f32_e32 v28, v148, v149
	v_pk_fma_f32 v[114:115], v[4:5], v[116:117], v[114:115]
	v_and_b32_e32 v151, 0xffff0000, v59
	v_pk_mul_f32 v[116:117], v[16:17], v[114:115]
	v_pk_add_f32 v[154:155], v[150:151], -1.0 op_sel_hi:[1,0]
	v_pk_mul_f32 v[142:143], v[116:117], v[116:117]
	s_waitcnt vmcnt(5)
	v_lshlrev_b32_e32 v160, 16, v88
	v_add_f32_e32 v28, v142, v28
	v_add_f32_e32 v28, v143, v28
	v_pk_fma_f32 v[142:143], v[20:21], v[154:155], 1.0 op_sel_hi:[1,1,0]
	v_and_b32_e32 v161, 0xffff0000, v88
	v_add_f32_dpp v28, v28, v28 row_ror:1 row_mask:0xf bank_mask:0xf bound_ctrl:1
	v_pk_mul_f32 v[142:143], v[142:143], v[114:115]
	v_pk_mul_f32 v[114:115], v[116:117], v[150:151]
	v_add_f32_dpp v28, v28, v28 row_ror:2 row_mask:0xf bank_mask:0xf bound_ctrl:1
	v_lshlrev_b32_e32 v162, 16, v89
	v_and_b32_e32 v163, 0xffff0000, v89
	v_add_f32_dpp v28, v28, v28 row_ror:4 row_mask:0xf bank_mask:0xf bound_ctrl:1
	v_pk_add_f32 v[108:109], v[108:109], v[160:161] neg_lo:[0,1] neg_hi:[0,1]
	v_pk_add_f32 v[110:111], v[110:111], v[162:163] neg_lo:[0,1] neg_hi:[0,1]
	v_add_f32_dpp v28, v28, v28 row_ror:8 row_mask:0xf bank_mask:0xf bound_ctrl:1
	v_max_f32_e32 v28, 0x179abe15, v28
	v_rsq_f32_e32 v28, v28
	v_pk_fma_f32 v[110:111], v[8:9], v[110:111], v[162:163]
	v_pk_fma_f32 v[108:109], v[6:7], v[108:109], v[160:161]
	v_pk_mul_f32 v[150:151], v[116:117], v[28:29] op_sel_hi:[1,0] neg_lo:[0,1] neg_hi:[0,1]
	v_lshlrev_b32_e32 v116, 16, v83
	v_and_b32_e32 v117, 0xffff0000, v83
	v_pk_add_f32 v[112:113], v[112:113], v[116:117] neg_lo:[0,1] neg_hi:[0,1]
	v_pk_mul_f32 v[154:155], v[114:115], v[28:29] op_sel_hi:[1,0]
	v_pk_fma_f32 v[158:159], v[12:13], v[112:113], v[116:117]
	v_pk_mul_f32 v[148:149], v[146:147], v[28:29] op_sel_hi:[1,0] neg_lo:[0,1] neg_hi:[0,1]
	v_pk_mul_f32 v[112:113], v[158:159], v[142:143]
	v_pk_mul_f32 v[114:115], v[158:159], v[114:115]
	v_fmac_f32_e32 v156, v24, v112
	v_add_f32_e32 v112, v112, v157
	v_add_f32_e32 v114, v114, v164
	v_cvt_f32_f16_sdwa v147, v53 dst_sel:DWORD dst_unused:UNUSED_PAD src0_sel:WORD_1
	v_cvt_f32_f16_e32 v146, v53
	v_fmac_f32_e32 v156, v25, v113
	v_add_f32_e32 v112, v113, v112
	v_add_f32_e32 v113, v115, v114
	v_add_f32_dpp v114, v156, v156 row_ror:1 row_mask:0xf bank_mask:0xf bound_ctrl:1
	v_add_f32_dpp v112, v112, v112 row_ror:1 row_mask:0xf bank_mask:0xf bound_ctrl:1
	v_add_f32_dpp v113, v113, v113 row_ror:1 row_mask:0xf bank_mask:0xf bound_ctrl:1
	v_add_f32_dpp v114, v114, v114 row_ror:2 row_mask:0xf bank_mask:0xf bound_ctrl:1
	v_add_f32_dpp v116, v112, v112 row_ror:2 row_mask:0xf bank_mask:0xf bound_ctrl:1
	v_add_f32_dpp v113, v113, v113 row_ror:2 row_mask:0xf bank_mask:0xf bound_ctrl:1
	v_add_f32_dpp v112, v114, v114 row_ror:4 row_mask:0xf bank_mask:0xf bound_ctrl:1
	v_add_f32_dpp v114, v116, v116 row_ror:4 row_mask:0xf bank_mask:0xf bound_ctrl:1
	v_add_f32_dpp v115, v113, v113 row_ror:4 row_mask:0xf bank_mask:0xf bound_ctrl:1
	v_mov_b32_e32 v116, 0
	v_mov_b32_e32 v117, 0
	v_mov_b32_e32 v113, 0
	v_pk_add_f32 v[146:147], v[146:147], 1.0 op_sel_hi:[1,0] neg_lo:[1,0] neg_hi:[1,0]
	v_mov_b32_dpp v116, v115 row_ror:8 row_mask:0xf bank_mask:0xf
	v_mov_b32_dpp v117, v114 row_ror:8 row_mask:0xf bank_mask:0xf
	v_mov_b32_dpp v113, v112 row_ror:8 row_mask:0xf bank_mask:0xf
	v_pk_mul_f32 v[152:153], v[152:153], v[28:29] op_sel_hi:[1,0]
	v_pk_mul_f32 v[156:157], v[118:119], 1.0 op_sel_hi:[1,0]
	v_pk_mul_f32 v[158:159], v[158:159], 1.0 op_sel_hi:[1,0]
	ds_write_b128 v129, v[144:147] offset:50176
	s_nop 7
	s_nop 7
	s_nop 7
	s_nop 7
	s_nop 7
	ds_write_b128 v129, v[140:143] offset:50432
	s_nop 7
	s_nop 7
	s_nop 7
	s_nop 7
	s_nop 7
	ds_write_b128 v129, v[148:151] offset:50688
	s_nop 7
	s_nop 7
	s_nop 7
	s_nop 7
	s_nop 7
	ds_write_b128 v129, v[152:155] offset:50944
	s_nop 7
	s_nop 7
	s_nop 7
	s_nop 7
	s_nop 7
	ds_write_b128 v129, v[156:159] offset:51200
	s_nop 7
	s_nop 7
	s_nop 7
	s_nop 7
	s_nop 7
	ds_write_b128 v129, v[108:111] offset:51456
	s_nop 7
	s_nop 7
	s_nop 7
	s_nop 7
	s_nop 7
	s_and_saveexec_b64 s[52:53], s[4:5]
	s_cbranch_execz .LBB0_1121
	v_add_f32_e32 v108, v115, v116
	v_mul_f32_e32 v108, v108, v28
	v_add_f32_e32 v109, v114, v117
	ds_write_b64 v128, v[108:109] offset:51712
	s_or_b64 exec, exec, s[52:53]
	s_and_saveexec_b64 s[52:53], s[44:45]
	s_cbranch_execnz .LBB0_1122

; #define LAS __attribute__((address_space(3)))
; __device__ __forceinline__ float scan_prepare(const ScanRegs& R, const u32x2 qr_, const u32x2 qk_, const u32x2 qv_, LAS float* slot, int cq, const f32x4 mur, const f32x4 muk, const f32x4 muv, const f32x4 kkc, const f32x4 kac, const f32x4 rkc) {
;     float pr[4], pk[4], pv[4], qr[4], qk[4], qv[4], av[4], om[4];
;     unpack4(R.pr, pr); unpack4(R.pk, pk); unpack4(R.pv, pv); unpack4(qr_, qr); unpack4(qk_, qk); unpack4(qv_, qv); unpack4(R.as, av);
;     om[0] = f16_to_f((unsigned short)(R.wl.x & 0xffffu)); om[1] = f16_to_f((unsigned short)(R.wl.x >> 16)); om[2] = f16_to_f((unsigned short)(R.wl.y & 0xffffu)); om[3] = f16_to_f((unsigned short)(R.wl.y >> 16));
;     float rr[4], vv[4], kn[4], k2[4], dec[4], bu[4];
;     float ssq = 0.f, bon = 0.f, c1 = 0.f, c2 = 0.f;
; #pragma unroll
;     for (int j = 0; j < 4; ++j) {
;         rr[j] = pr[j] + (qr[j] - pr[j]) * mur[j]; const float kk0 = pk[j] + (qk[j] - pk[j]) * muk[j]; vv[j] = pv[j] + (qv[j] - pv[j]) * muv[j];
;         dec[j] = 1.0f - om[j];
;         kn[j] = kk0 * kkc[j]; ssq += kn[j] * kn[j];
;         k2[j] = kk0 * (1.0f + (av[j] - 1.0f) * kac[j]);
;         const float t = rr[j] * k2[j]; bon += t * rkc[j]; c2 += t;
;         bu[j] = kn[j] * av[j]; c1 += bu[j] * rr[j];
;     }
;     ssq += dpp_f<0x121>(ssq); bon += dpp_f<0x121>(bon); c1 += dpp_f<0x121>(c1); c2 += dpp_f<0x121>(c2);
;     ssq += dpp_f<0x122>(ssq); bon += dpp_f<0x122>(bon); c1 += dpp_f<0x122>(c1); c2 += dpp_f<0x122>(c2);
;     ssq += dpp_f<0x124>(ssq); bon += dpp_f<0x124>(bon); c1 += dpp_f<0x124>(c1); c2 += dpp_f<0x124>(c2);
;     ssq += dpp_f<0x128>(ssq); bon += dpp_f<0x128>(bon); c1 += dpp_f<0x128>(c1); c2 += dpp_f<0x128>(c2);
;     const float inv = __builtin_amdgcn_rsqf(fmaxf(ssq, 1e-24f));
;     f32x4 o_al, o_be, o_wr;
; #pragma unroll
;     for (int j = 0; j < 4; ++j) { o_al[j] = -(kn[j] * inv); o_be[j] = bu[j] * inv; o_wr[j] = dec[j] * rr[j]; }
;     LAS f32x4* s4 = (LAS f32x4*)slot;
;     s4[cq] = (f32x4){dec[0], dec[1], dec[2], dec[3]}; s4[16 + cq] = (f32x4){k2[0], k2[1], k2[2], k2[3]}; s4[32 + cq] = o_al; s4[48 + cq] = o_be; s4[64 + cq] = o_wr;
;     s4[80 + cq] = (f32x4){vv[0], vv[1], vv[2], vv[3]};
;     if (cq == 0) *(LAS f32x2*)(slot + 384) = (f32x2){c1 * inv, c2};
;     return bon;
; }
.LBB0_1115:
	v_add_u32_e32 v28, v120, v130
	s_waitcnt lgkmcnt(0)
	s_barrier
	ds_read_b128 v[108:111], v28
	v_lshl_add_u64 v[112:113], s[92:93], 0, v[100:101]
	v_add_co_u32_e32 v112, vcc, s68, v112
	s_cmpk_gt_u32 s14, 0xfd
	s_waitcnt lgkmcnt(0)
	v_add_f32_e32 v28, v108, v109
	v_add_f32_e32 v33, v110, v111
	v_add_f32_e32 v28, v28, v33
	v_bfe_u32 v33, v28, 16, 1
	v_add3_u32 v28, v28, v33, s67
	v_addc_co_u32_e32 v113, vcc, 0, v113, vcc
	global_store_short_d16_hi v[112:113], v28, off
	v_add_u32_e32 v28, v120, v131
	ds_read_b128 v[108:111], v28
	s_cselect_b64 s[52:53], -1, 0
	s_and_b64 vcc, exec, s[52:53]
	s_waitcnt lgkmcnt(0)
	v_add_f32_e32 v28, v108, v109
	v_add_f32_e32 v33, v110, v111
	v_add_f32_e32 v28, v28, v33
	v_bfe_u32 v33, v28, 16, 1
	v_add3_u32 v28, v28, v33, s67
	global_store_short_d16_hi v[112:113], v28, off offset:2048
	s_cbranch_vccnz .LBB0_1106
	v_lshlrev_b32_e32 v108, 16, v76
	v_and_b32_e32 v109, 0xffff0000, v76
	v_lshlrev_b32_e32 v110, 16, v62
	v_and_b32_e32 v111, 0xffff0000, v62
	v_pk_add_f32 v[110:111], v[110:111], v[108:109] neg_lo:[0,1] neg_hi:[0,1]
	v_lshlrev_b32_e32 v140, 16, v63
	v_pk_fma_f32 v[144:145], v[6:7], v[110:111], v[108:109]
	v_lshlrev_b32_e32 v110, 16, v77
	v_and_b32_e32 v111, 0xffff0000, v77
	v_and_b32_e32 v141, 0xffff0000, v63
	v_pk_add_f32 v[140:141], v[140:141], v[110:111] neg_lo:[0,1] neg_hi:[0,1]
	v_lshlrev_b32_e32 v118, 16, v64
	v_and_b32_e32 v119, 0xffff0000, v64
	v_pk_fma_f32 v[146:147], v[8:9], v[140:141], v[110:111]
	v_lshlrev_b32_e32 v140, 16, v54
	v_and_b32_e32 v141, 0xffff0000, v54
	s_waitcnt vmcnt(3)
	v_lshlrev_b32_e32 v142, 16, v86
	v_and_b32_e32 v143, 0xffff0000, v86
	v_pk_add_f32 v[140:141], v[140:141], v[118:119] neg_lo:[0,1] neg_hi:[0,1]
	v_pk_add_f32 v[148:149], v[142:143], -1.0 op_sel_hi:[1,0]
	v_pk_fma_f32 v[140:141], v[2:3], v[140:141], v[118:119]
	v_pk_fma_f32 v[148:149], v[18:19], v[148:149], 1.0 op_sel_hi:[1,1,0]
	v_pk_mul_f32 v[154:155], v[14:15], v[140:141]
	v_pk_mul_f32 v[148:149], v[140:141], v[148:149]
	v_cvt_f32_f16_sdwa v141, v72 dst_sel:DWORD dst_unused:UNUSED_PAD src0_sel:WORD_1
	v_cvt_f32_f16_e32 v140, v72
	v_lshlrev_b32_e32 v114, 16, v56
	v_and_b32_e32 v115, 0xffff0000, v56
	v_lshlrev_b32_e32 v156, 16, v68
	v_and_b32_e32 v157, 0xffff0000, v68
	v_pk_add_f32 v[152:153], v[140:141], 1.0 op_sel_hi:[1,0] neg_lo:[1,0] neg_hi:[1,0]
	v_pk_add_f32 v[140:141], v[156:157], v[114:115] neg_lo:[0,1] neg_hi:[0,1]
	v_lshlrev_b32_e32 v116, 16, v65
	v_pk_fma_f32 v[164:165], v[10:11], v[140:141], v[114:115]
	v_and_b32_e32 v117, 0xffff0000, v65
	v_pk_mul_f32 v[140:141], v[164:165], v[148:149]
	v_pk_mul_f32 v[150:151], v[154:155], v[154:155]
	v_fma_f32 v33, v22, v140, 0
	v_add_f32_e32 v28, 0, v140
	v_fmac_f32_e32 v33, v23, v141
	v_add_f32_e32 v168, v141, v28
	v_lshlrev_b32_e32 v140, 16, v55
	v_and_b32_e32 v141, 0xffff0000, v55
	v_pk_add_f32 v[140:141], v[140:141], v[116:117] neg_lo:[0,1] neg_hi:[0,1]
	v_add_f32_e32 v28, v150, v151
	v_pk_fma_f32 v[140:141], v[4:5], v[140:141], v[116:117]
	v_pk_mul_f32 v[142:143], v[154:155], v[142:143]
	v_pk_mul_f32 v[158:159], v[16:17], v[140:141]
	v_pk_mul_f32 v[156:157], v[164:165], v[142:143]
	v_pk_mul_f32 v[160:161], v[158:159], v[158:159]
	v_add_f32_e32 v81, 0, v156
	v_add_f32_e32 v28, v160, v28
	v_add_f32_e32 v28, v161, v28
	v_add_f32_e32 v81, v157, v81
	v_lshlrev_b32_e32 v156, 16, v87
	v_add_f32_dpp v28, v28, v28 row_ror:1 row_mask:0xf bank_mask:0xf bound_ctrl:1
	v_and_b32_e32 v157, 0xffff0000, v87
	v_lshlrev_b32_e32 v112, 16, v57
	v_add_f32_dpp v28, v28, v28 row_ror:2 row_mask:0xf bank_mask:0xf bound_ctrl:1
	v_and_b32_e32 v113, 0xffff0000, v57
	v_pk_add_f32 v[162:163], v[156:157], -1.0 op_sel_hi:[1,0]
	v_add_f32_dpp v28, v28, v28 row_ror:4 row_mask:0xf bank_mask:0xf bound_ctrl:1
	v_pk_fma_f32 v[150:151], v[20:21], v[162:163], 1.0 op_sel_hi:[1,1,0]
	v_pk_mul_f32 v[164:165], v[164:165], 1.0 op_sel_hi:[1,0]
	v_add_f32_dpp v28, v28, v28 row_ror:8 row_mask:0xf bank_mask:0xf bound_ctrl:1
	v_max_f32_e32 v28, 0x179abe15, v28
	v_rsq_f32_e32 v28, v28
	v_pk_mul_f32 v[150:151], v[140:141], v[150:151]
	v_pk_mul_f32 v[140:141], v[158:159], v[156:157]
	v_pk_mul_f32 v[160:161], v[142:143], v[28:29] op_sel_hi:[1,0]
	v_lshlrev_b32_e32 v142, 16, v69
	v_and_b32_e32 v143, 0xffff0000, v69
	v_pk_add_f32 v[142:143], v[142:143], v[112:113] neg_lo:[0,1] neg_hi:[0,1]
	v_pk_mul_f32 v[162:163], v[140:141], v[28:29] op_sel_hi:[1,0]
	v_pk_fma_f32 v[166:167], v[12:13], v[142:143], v[112:113]
	v_pk_mul_f32 v[156:157], v[154:155], v[28:29] op_sel_hi:[1,0] neg_lo:[0,1] neg_hi:[0,1]
	v_pk_mul_f32 v[142:143], v[166:167], v[150:151]
	v_pk_mul_f32 v[140:141], v[166:167], v[140:141]
	v_fmac_f32_e32 v33, v24, v142
	v_add_f32_e32 v142, v142, v168
	v_add_f32_e32 v81, v140, v81
	v_cvt_f32_f16_sdwa v155, v73 dst_sel:DWORD dst_unused:UNUSED_PAD src0_sel:WORD_1
	v_cvt_f32_f16_e32 v154, v73
	v_fmac_f32_e32 v33, v25, v143
	v_add_f32_e32 v140, v143, v142
	v_add_f32_e32 v81, v141, v81
	v_add_f32_dpp v33, v33, v33 row_ror:1 row_mask:0xf bank_mask:0xf bound_ctrl:1
	v_add_f32_dpp v140, v140, v140 row_ror:1 row_mask:0xf bank_mask:0xf bound_ctrl:1
	v_add_f32_dpp v81, v81, v81 row_ror:1 row_mask:0xf bank_mask:0xf bound_ctrl:1
	v_add_f32_dpp v33, v33, v33 row_ror:2 row_mask:0xf bank_mask:0xf bound_ctrl:1
	v_add_f32_dpp v140, v140, v140 row_ror:2 row_mask:0xf bank_mask:0xf bound_ctrl:1
	v_add_f32_dpp v81, v81, v81 row_ror:2 row_mask:0xf bank_mask:0xf bound_ctrl:1
	v_add_f32_dpp v33, v33, v33 row_ror:4 row_mask:0xf bank_mask:0xf bound_ctrl:1
	v_add_f32_dpp v140, v140, v140 row_ror:4 row_mask:0xf bank_mask:0xf bound_ctrl:1
	v_add_f32_dpp v141, v81, v81 row_ror:4 row_mask:0xf bank_mask:0xf bound_ctrl:1
	v_mov_b32_e32 v142, 0
	v_mov_b32_e32 v143, 0
	v_mov_b32_e32 v81, 0
	v_pk_add_f32 v[154:155], v[154:155], 1.0 op_sel_hi:[1,0] neg_lo:[1,0] neg_hi:[1,0]
	v_mov_b32_dpp v142, v141 row_ror:8 row_mask:0xf bank_mask:0xf
	v_mov_b32_dpp v143, v140 row_ror:8 row_mask:0xf bank_mask:0xf
	v_mov_b32_dpp v81, v33 row_ror:8 row_mask:0xf bank_mask:0xf
	v_pk_mul_f32 v[158:159], v[158:159], v[28:29] op_sel_hi:[1,0] neg_lo:[0,1] neg_hi:[0,1]
	v_pk_mul_f32 v[166:167], v[166:167], 1.0 op_sel_hi:[1,0]
	ds_write_b128 v127, v[152:155]
	s_nop 7
	s_nop 7
	s_nop 7
	s_nop 7
	s_nop 7
	ds_write_b128 v127, v[148:151] offset:256
	s_nop 7
	s_nop 7
	s_nop 7
	s_nop 7
	s_nop 7
	ds_write_b128 v127, v[156:159] offset:512
	s_nop 7
	s_nop 7
	s_nop 7
	s_nop 7
	s_nop 7
	ds_write_b128 v127, v[160:163] offset:768
	s_nop 7
	s_nop 7
	s_nop 7
	s_nop 7
	s_nop 7
	ds_write_b128 v127, v[164:167] offset:1024
	s_nop 7
	s_nop 7
	s_nop 7
	s_nop 7
	s_nop 7
	ds_write_b128 v127, v[144:147] offset:1280
	s_nop 7
	s_nop 7
	s_nop 7
	s_nop 7
	s_nop 7
	s_and_saveexec_b64 s[56:57], s[4:5]
	v_add_f32_e32 v141, v141, v142
	v_mul_f32_e32 v142, v141, v28
	v_add_f32_e32 v143, v140, v143
	ds_write_b64 v126, v[142:143] offset:1536
	s_or_b64 exec, exec, s[56:57]
	s_waitcnt vmcnt(4)
; #define LAS __attribute__((address_space(3)))
; __device__ __forceinline__ float scan_prepare(const ScanRegs& R, const u32x2 qr_, const u32x2 qk_, const u32x2 qv_, LAS float* slot, int cq, const f32x4 mur, const f32x4 muk, const f32x4 muv, const f32x4 kkc, const f32x4 kac, const f32x4 rkc) {
;     float pr[4], pk[4], pv[4], qr[4], qk[4], qv[4], av[4], om[4];
;     unpack4(R.pr, pr); unpack4(R.pk, pk); unpack4(R.pv, pv); unpack4(qr_, qr); unpack4(qk_, qk); unpack4(qv_, qv); unpack4(R.as, av);
;     om[0] = f16_to_f((unsigned short)(R.wl.x & 0xffffu)); om[1] = f16_to_f((unsigned short)(R.wl.x >> 16)); om[2] = f16_to_f((unsigned short)(R.wl.y & 0xffffu)); om[3] = f16_to_f((unsigned short)(R.wl.y >> 16));
;     float rr[4], vv[4], kn[4], k2[4], dec[4], bu[4];
;     float ssq = 0.f, bon = 0.f, c1 = 0.f, c2 = 0.f;
; #pragma unroll
;     for (int j = 0; j < 4; ++j) {
;         rr[j] = pr[j] + (qr[j] - pr[j]) * mur[j]; const float kk0 = pk[j] + (qk[j] - pk[j]) * muk[j]; vv[j] = pv[j] + (qv[j] - pv[j]) * muv[j];
;         dec[j] = 1.0f - om[j];
;         kn[j] = kk0 * kkc[j]; ssq += kn[j] * kn[j];
;         k2[j] = kk0 * (1.0f + (av[j] - 1.0f) * kac[j]);
;         const float t = rr[j] * k2[j]; bon += t * rkc[j]; c2 += t;
;         bu[j] = kn[j] * av[j]; c1 += bu[j] * rr[j];
;     }
;     ssq += dpp_f<0x121>(ssq); bon += dpp_f<0x121>(bon); c1 += dpp_f<0x121>(c1); c2 += dpp_f<0x121>(c2);
;     ssq += dpp_f<0x122>(ssq); bon += dpp_f<0x122>(bon); c1 += dpp_f<0x122>(c1); c2 += dpp_f<0x122>(c2);
;     ssq += dpp_f<0x124>(ssq); bon += dpp_f<0x124>(bon); c1 += dpp_f<0x124>(c1); c2 += dpp_f<0x124>(c2);
;     ssq += dpp_f<0x128>(ssq); bon += dpp_f<0x128>(bon); c1 += dpp_f<0x128>(c1); c2 += dpp_f<0x128>(c2);
;     const float inv = __builtin_amdgcn_rsqf(fmaxf(ssq, 1e-24f));
;     f32x4 o_al, o_be, o_wr;
; #pragma unroll
;     for (int j = 0; j < 4; ++j) { o_al[j] = -(kn[j] * inv); o_be[j] = bu[j] * inv; o_wr[j] = dec[j] * rr[j]; }
;     LAS f32x4* s4 = (LAS f32x4*)slot;
;     s4[cq] = (f32x4){dec[0], dec[1], dec[2], dec[3]}; s4[16 + cq] = (f32x4){k2[0], k2[1], k2[2], k2[3]}; s4[32 + cq] = o_al; s4[48 + cq] = o_be; s4[64 + cq] = o_wr;
;     s4[80 + cq] = (f32x4){vv[0], vv[1], vv[2], vv[3]};
;     if (cq == 0) *(LAS f32x2*)(slot + 384) = (f32x2){c1 * inv, c2};
;     return bon;
; }
	v_lshlrev_b32_e32 v140, 16, v96
	v_and_b32_e32 v141, 0xffff0000, v96
	s_waitcnt vmcnt(2)
	v_lshlrev_b32_e32 v142, 16, v102
	v_and_b32_e32 v143, 0xffff0000, v102
	v_pk_add_f32 v[118:119], v[118:119], v[140:141] neg_lo:[0,1] neg_hi:[0,1]
	v_lshlrev_b32_e32 v150, 16, v103
	v_pk_fma_f32 v[118:119], v[2:3], v[118:119], v[140:141]
	v_pk_add_f32 v[140:141], v[142:143], -1.0 op_sel_hi:[1,0]
	v_pk_mul_f32 v[146:147], v[14:15], v[118:119]
	v_pk_fma_f32 v[140:141], v[18:19], v[140:141], 1.0 op_sel_hi:[1,1,0]
	v_pk_mul_f32 v[152:153], v[146:147], v[142:143]
	v_pk_mul_f32 v[140:141], v[140:141], v[118:119]
	v_cvt_f32_f16_sdwa v119, v98 dst_sel:DWORD dst_unused:UNUSED_PAD src0_sel:WORD_1
	v_cvt_f32_f16_e32 v118, v98
	v_lshlrev_b32_e32 v142, 16, v84
	v_and_b32_e32 v143, 0xffff0000, v84
	v_pk_add_f32 v[114:115], v[114:115], v[142:143] neg_lo:[0,1] neg_hi:[0,1]
	v_pk_add_f32 v[144:145], v[118:119], 1.0 op_sel_hi:[1,0] neg_lo:[1,0] neg_hi:[1,0]
	v_pk_fma_f32 v[118:119], v[10:11], v[114:115], v[142:143]
	v_pk_mul_f32 v[148:149], v[146:147], v[146:147]
	v_pk_mul_f32 v[114:115], v[118:119], v[140:141]
	v_pk_mul_f32 v[142:143], v[118:119], v[152:153]
	v_fma_f32 v156, v22, v114, 0
	v_add_f32_e32 v28, 0, v114
	v_add_f32_e32 v114, 0, v142
	v_fmac_f32_e32 v156, v23, v115
	v_add_f32_e32 v157, v115, v28
	v_add_f32_e32 v164, v143, v114
	v_lshlrev_b32_e32 v114, 16, v97
	v_and_b32_e32 v115, 0xffff0000, v97
	v_pk_add_f32 v[116:117], v[116:117], v[114:115] neg_lo:[0,1] neg_hi:[0,1]
	v_add_f32_e32 v28, v148, v149
	v_pk_fma_f32 v[114:115], v[4:5], v[116:117], v[114:115]
	v_and_b32_e32 v151, 0xffff0000, v103
	v_pk_mul_f32 v[116:117], v[16:17], v[114:115]
	v_pk_add_f32 v[154:155], v[150:151], -1.0 op_sel_hi:[1,0]
	v_pk_mul_f32 v[142:143], v[116:117], v[116:117]
	v_lshlrev_b32_e32 v160, 16, v94
	v_add_f32_e32 v28, v142, v28
	v_add_f32_e32 v28, v143, v28
	v_pk_fma_f32 v[142:143], v[20:21], v[154:155], 1.0 op_sel_hi:[1,1,0]
	v_and_b32_e32 v161, 0xffff0000, v94
	v_add_f32_dpp v28, v28, v28 row_ror:1 row_mask:0xf bank_mask:0xf bound_ctrl:1
	v_pk_mul_f32 v[142:143], v[142:143], v[114:115]
	v_pk_mul_f32 v[114:115], v[116:117], v[150:151]
	v_add_f32_dpp v28, v28, v28 row_ror:2 row_mask:0xf bank_mask:0xf bound_ctrl:1
	v_lshlrev_b32_e32 v162, 16, v95
	v_and_b32_e32 v163, 0xffff0000, v95
	v_add_f32_dpp v28, v28, v28 row_ror:4 row_mask:0xf bank_mask:0xf bound_ctrl:1
	v_pk_add_f32 v[108:109], v[108:109], v[160:161] neg_lo:[0,1] neg_hi:[0,1]
	v_pk_add_f32 v[110:111], v[110:111], v[162:163] neg_lo:[0,1] neg_hi:[0,1]
	v_add_f32_dpp v28, v28, v28 row_ror:8 row_mask:0xf bank_mask:0xf bound_ctrl:1
	v_max_f32_e32 v28, 0x179abe15, v28
	v_rsq_f32_e32 v28, v28
	v_pk_fma_f32 v[110:111], v[8:9], v[110:111], v[162:163]
	v_pk_fma_f32 v[108:109], v[6:7], v[108:109], v[160:161]
	v_pk_mul_f32 v[150:151], v[116:117], v[28:29] op_sel_hi:[1,0] neg_lo:[0,1] neg_hi:[0,1]
	v_lshlrev_b32_e32 v116, 16, v85
	v_and_b32_e32 v117, 0xffff0000, v85
	v_pk_add_f32 v[112:113], v[112:113], v[116:117] neg_lo:[0,1] neg_hi:[0,1]
	v_pk_mul_f32 v[154:155], v[114:115], v[28:29] op_sel_hi:[1,0]
	v_pk_fma_f32 v[158:159], v[12:13], v[112:113], v[116:117]
	v_pk_mul_f32 v[148:149], v[146:147], v[28:29] op_sel_hi:[1,0] neg_lo:[0,1] neg_hi:[0,1]
	v_pk_mul_f32 v[112:113], v[158:159], v[142:143]
	v_pk_mul_f32 v[114:115], v[158:159], v[114:115]
	v_fmac_f32_e32 v156, v24, v112
	v_add_f32_e32 v112, v112, v157
	v_add_f32_e32 v114, v114, v164
	v_cvt_f32_f16_sdwa v147, v99 dst_sel:DWORD dst_unused:UNUSED_PAD src0_sel:WORD_1
	v_cvt_f32_f16_e32 v146, v99
	v_fmac_f32_e32 v156, v25, v113
	v_add_f32_e32 v112, v113, v112
	v_add_f32_e32 v113, v115, v114
	v_add_f32_dpp v114, v156, v156 row_ror:1 row_mask:0xf bank_mask:0xf bound_ctrl:1
	v_add_f32_dpp v112, v112, v112 row_ror:1 row_mask:0xf bank_mask:0xf bound_ctrl:1
	v_add_f32_dpp v113, v113, v113 row_ror:1 row_mask:0xf bank_mask:0xf bound_ctrl:1
	v_add_f32_dpp v114, v114, v114 row_ror:2 row_mask:0xf bank_mask:0xf bound_ctrl:1
	v_add_f32_dpp v116, v112, v112 row_ror:2 row_mask:0xf bank_mask:0xf bound_ctrl:1
	v_add_f32_dpp v113, v113, v113 row_ror:2 row_mask:0xf bank_mask:0xf bound_ctrl:1
	v_add_f32_dpp v112, v114, v114 row_ror:4 row_mask:0xf bank_mask:0xf bound_ctrl:1
	v_add_f32_dpp v114, v116, v116 row_ror:4 row_mask:0xf bank_mask:0xf bound_ctrl:1
	v_add_f32_dpp v115, v113, v113 row_ror:4 row_mask:0xf bank_mask:0xf bound_ctrl:1
	v_mov_b32_e32 v116, 0
	v_mov_b32_e32 v117, 0
	v_mov_b32_e32 v113, 0
	v_pk_add_f32 v[146:147], v[146:147], 1.0 op_sel_hi:[1,0] neg_lo:[1,0] neg_hi:[1,0]
	v_mov_b32_dpp v116, v115 row_ror:8 row_mask:0xf bank_mask:0xf
	v_mov_b32_dpp v117, v114 row_ror:8 row_mask:0xf bank_mask:0xf
	v_mov_b32_dpp v113, v112 row_ror:8 row_mask:0xf bank_mask:0xf
	v_pk_mul_f32 v[152:153], v[152:153], v[28:29] op_sel_hi:[1,0]
	v_pk_mul_f32 v[156:157], v[118:119], 1.0 op_sel_hi:[1,0]
	v_pk_mul_f32 v[158:159], v[158:159], 1.0 op_sel_hi:[1,0]
	ds_write_b128 v129, v[144:147]
	s_nop 7
	s_nop 7
	s_nop 7
	s_nop 7
	s_nop 7
	ds_write_b128 v129, v[140:143] offset:256
	s_nop 7
	s_nop 7
	s_nop 7
	s_nop 7
	s_nop 7
	ds_write_b128 v129, v[148:151] offset:512
	s_nop 7
	s_nop 7
	s_nop 7
	s_nop 7
	s_nop 7
	ds_write_b128 v129, v[152:155] offset:768
	s_nop 7
	s_nop 7
	s_nop 7
	s_nop 7
	s_nop 7
	ds_write_b128 v129, v[156:159] offset:1024
	s_nop 7
	s_nop 7
	s_nop 7
	s_nop 7
	s_nop 7
	ds_write_b128 v129, v[108:111] offset:1280
	s_nop 7
	s_nop 7
	s_nop 7
	s_nop 7
	s_nop 7
	s_and_saveexec_b64 s[56:57], s[4:5]
	s_cbranch_execz .LBB0_1123
	v_add_f32_e32 v108, v115, v116
	v_mul_f32_e32 v108, v108, v28
	v_add_f32_e32 v109, v114, v117
	ds_write_b64 v128, v[108:109] offset:1536
	s_or_b64 exec, exec, s[56:57]
	s_and_saveexec_b64 s[56:57], s[44:45]
	s_cbranch_execnz .LBB0_1124
